# v41: v36 + int8 GEMM1: trailing wave half's per-unit restore barrier moved after its unit preamble (index math + accumulator clears overlap the leading half's first load segment)
# speedup vs baseline: 1.0080x; 1.0080x over previous
.LBB0_294:
	s_mul_i32 s92, s24, 0x3000
	v_readlane_b32 s40, v251, 8
	s_lshl_b64 s[22:23], s[92:93], 2
	v_readlane_b32 s48, v251, 16
	v_readlane_b32 s55, v251, 23
	v_readlane_b32 s49, v251, 17
	s_add_u32 s55, s48, s22
	s_addc_u32 s15, s49, s23
	s_mul_i32 s92, s24, 0x7000
	v_writelane_b32 v255, s15, 12
	s_lshl_b64 s[22:23], s[92:93], 2
	v_readlane_b32 s15, v251, 4
	s_add_u32 s24, s15, s22
	v_readlane_b32 s15, v251, 5
	s_addc_u32 s25, s15, s23
	s_and_b32 s26, s19, 3
	v_and_b32_e32 v16, 48, v15
	v_lshlrev_b32_e32 v17, 6, v15
	s_movk_i32 s15, 0x3c0
	v_lshlrev_b32_e32 v15, 2, v15
	s_lshl_b32 s77, s14, 6
	s_lshl_b32 s14, s14, 13
	v_and_or_b32 v16, v17, s15, v16
	v_and_b32_e32 v15, 32, v15
	s_lshl_b32 s15, s26, 12
	s_add_i32 m0, s21, 0x18000
	v_lshl_add_u64 v[8:9], v[8:9], 0, s[12:13]
	v_bitop3_b32 v17, v16, s14, v15 bitop3:0xde
	s_lshl_b32 s14, s26, 5
	v_bitop3_b32 v199, v16, s15, v15 bitop3:0xde
	s_waitcnt vmcnt(2)
	s_barrier
	global_load_lds_dwordx4 v[8:9], off
	v_lshl_add_u64 v[6:7], v[6:7], 0, s[12:13]
	s_add_i32 m0, s21, 0x1a000
	s_add_i32 s15, s21, 0x8000
	s_add_i32 s88, s21, 0xa000
	global_load_lds_dwordx4 v[6:7], off
	v_lshl_add_u64 v[2:3], v[2:3], 0, s[12:13]
	s_mov_b32 m0, s15
	s_add_u32 s22, s28, 0x80080
	global_load_lds_dwordx4 v[2:3], off
	v_lshl_add_u64 v[2:3], v[4:5], 0, s[12:13]
	s_mov_b32 m0, s88
	s_addc_u32 s23, s29, 0
	global_load_lds_dwordx4 v[2:3], off
	s_add_i32 m0, s21, 0x1c000
	v_lshl_add_u64 v[2:3], s[22:23], 0, v[164:165]
	global_load_lds_dwordx4 v[2:3], off
	v_lshl_add_u64 v[2:3], s[22:23], 0, v[168:169]
	s_add_i32 m0, s21, 0x1e000
	v_readlane_b32 s52, v251, 20
	global_load_lds_dwordx4 v[2:3], off
	v_readlane_b32 s53, v251, 21
	s_cmpk_lt_u32 s9, 0x100
	s_cselect_b64 s[52:53], -1, 0
	s_cmp_eq_u32 s26, 0
	s_cselect_b64 s[22:23], -1, 0
	v_cndmask_b32_e64 v2, 0, 1, s[22:23]
	s_cmp_lt_u32 s26, 2
	s_mov_b32 s22, 0xa000000
	s_cselect_b32 s22, s22, 0x8000000
	s_cmp_gt_u32 s26, 1
	s_cselect_b64 s[34:35], -1, 0
	s_lshl_b32 s23, s26, 7
	v_readlane_b32 s50, v251, 18
	s_add_u32 s66, s24, s23
	s_addc_u32 s67, s25, 0
	s_lshl_b32 s50, s18, 2
	v_readfirstlane_b32 s9, v2
	v_cvt_f32_u32_e32 v2, s50
	v_readlane_b32 s18, v251, 30
	s_add_u32 s18, s18, s22
	v_readlane_b32 s22, v251, 31
	v_rcp_iflag_f32_e32 v2, v2
	s_addc_u32 s22, s22, 0
	s_lshl_b32 s19, s19, 6
	s_and_b32 s19, s19, 64
	v_mul_f32_e32 v2, 0x4f7ffffe, v2
	v_cvt_u32_f32_e32 v2, v2
	s_add_u32 s18, s18, s19
	v_writelane_b32 v255, s34, 14
	v_readlane_b32 s44, v251, 12
	v_readfirstlane_b32 s19, v2
	v_lshlrev_b32_e32 v2, 15, v0
	v_and_b32_e32 v2, 0xffff0000, v2
	v_lshl_add_u32 v2, v10, 12, v2
	v_and_b32_e32 v0, 1, v0
	v_writelane_b32 v255, s35, 15
	v_lshl_or_b32 v0, v0, 6, v2
	v_writelane_b32 v255, s18, 16
	s_addc_u32 s18, s22, 0
	v_lshl_add_u32 v170, v11, 1, v0
	v_lshlrev_b32_e32 v0, 15, v12
	v_writelane_b32 v255, s18, 17
	s_sub_i32 s18, 0, s50
	v_and_b32_e32 v0, 0xffff0000, v0
	v_readlane_b32 s45, v251, 13
	s_waitcnt vmcnt(6)
	s_mul_i32 s18, s18, s19
	v_lshl_add_u32 v0, v13, 12, v0
	v_and_b32_e32 v2, 1, v12
	v_readlane_b32 s46, v251, 14
	v_readlane_b32 s47, v251, 15
	v_readlane_b32 s51, v251, 19
	v_readlane_b32 s54, v251, 22
	s_mul_hi_u32 s18, s19, s18
	v_lshl_or_b32 v0, v2, 6, v0
	v_readlane_b32 s44, v251, 6
	s_mov_b32 s89, 0
	s_mov_b32 s37, s93
	s_add_i32 s51, s19, s18
	v_mov_b32_e32 v171, v1
	v_lshl_add_u32 v172, v14, 1, v0
	v_mov_b32_e32 v173, v1
	v_add_u32_e32 v250, 0, v17
	v_readlane_b32 s45, v251, 7
	v_readlane_b32 s92, v255, 3
	s_mov_b32 s54, 0x5c401000
	s_mov_b64 s[46:47], s[30:31]
	v_readlane_b32 s41, v251, 9
	v_readlane_b32 s42, v251, 10
	v_readlane_b32 s43, v251, 11
	s_barrier
	s_mov_b32 s100, 0
	s_branch .LBB0_297

.LBB0_299:
	s_ashr_i32 s49, s48, 31
	s_lshl_b64 s[18:19], s[48:49], 20
	s_add_u32 s22, s92, s18
	v_readlane_b32 s18, v251, 32
	s_addc_u32 s23, s18, s19
	s_and_b64 s[18:19], s[38:39], exec
	s_cselect_b32 s18, s23, s1
	s_cselect_b32 s19, s22, s0
	s_ashr_i32 s27, s26, 31
	s_lshl_b64 s[24:25], s[26:27], 20
	s_add_u32 s24, s80, s24
	s_addc_u32 s25, s33, s25
	s_and_b64 s[30:31], s[38:39], exec
	s_cselect_b32 s27, s25, s29
	s_cselect_b32 s34, s24, s28
	s_add_u32 s0, s0, 0x80080
	s_addc_u32 s1, s1, 0
	s_add_u32 s35, s28, 0x100
	v_mov_b64_e32 v[18:19], 0
	v_mov_b64_e32 v[20:21], 0
	v_mov_b64_e32 v[22:23], 0
	v_mov_b64_e32 v[24:25], 0
	v_mov_b64_e32 v[26:27], 0
	v_mov_b64_e32 v[28:29], 0
	v_mov_b64_e32 v[30:31], 0
	v_mov_b64_e32 v[32:33], 0
	v_mov_b64_e32 v[34:35], 0
	v_mov_b64_e32 v[36:37], 0
	v_mov_b64_e32 v[38:39], 0
	v_mov_b64_e32 v[40:41], 0
	v_mov_b64_e32 v[42:43], 0
	v_mov_b64_e32 v[44:45], 0
	v_mov_b64_e32 v[46:47], 0
	v_mov_b64_e32 v[48:49], 0
	v_mov_b64_e32 v[50:51], 0
	v_mov_b64_e32 v[52:53], 0
	v_mov_b64_e32 v[54:55], 0
	v_mov_b64_e32 v[56:57], 0
	v_mov_b64_e32 v[58:59], 0
	v_mov_b64_e32 v[60:61], 0
	v_mov_b64_e32 v[62:63], 0
	v_mov_b64_e32 v[64:65], 0
	v_mov_b64_e32 v[66:67], 0
	v_mov_b64_e32 v[68:69], 0
	v_mov_b64_e32 v[70:71], 0
	v_mov_b64_e32 v[72:73], 0
	v_mov_b64_e32 v[74:75], 0
	v_mov_b64_e32 v[76:77], 0
	v_mov_b64_e32 v[78:79], 0
	v_mov_b64_e32 v[80:81], 0
	v_mov_b64_e32 v[82:83], 0
	v_mov_b64_e32 v[84:85], 0
	v_mov_b64_e32 v[86:87], 0
	v_mov_b64_e32 v[88:89], 0
	v_mov_b64_e32 v[90:91], 0
	v_mov_b64_e32 v[92:93], 0
	v_mov_b64_e32 v[94:95], 0
	v_mov_b64_e32 v[96:97], 0
	v_mov_b64_e32 v[98:99], 0
	v_mov_b64_e32 v[100:101], 0
	v_mov_b64_e32 v[102:103], 0
	v_mov_b64_e32 v[104:105], 0
	v_mov_b64_e32 v[106:107], 0
	v_mov_b64_e32 v[108:109], 0
	v_mov_b64_e32 v[110:111], 0
	v_mov_b64_e32 v[112:113], 0
	v_mov_b64_e32 v[114:115], 0
	v_mov_b64_e32 v[116:117], 0
	v_mov_b64_e32 v[118:119], 0
	v_mov_b64_e32 v[120:121], 0
	v_mov_b64_e32 v[122:123], 0
	v_mov_b64_e32 v[124:125], 0
	v_mov_b64_e32 v[126:127], 0
	v_mov_b64_e32 v[128:129], 0
	v_mov_b64_e32 v[130:131], 0
	v_mov_b64_e32 v[132:133], 0
	v_mov_b64_e32 v[134:135], 0
	v_mov_b64_e32 v[136:137], 0
	v_mov_b64_e32 v[138:139], 0
	v_mov_b64_e32 v[140:141], 0
	v_mov_b64_e32 v[142:143], 0
	v_mov_b64_e32 v[144:145], 0
	s_addc_u32 s40, s29, 0
	s_mov_b32 s41, -2
	s_cmp_eq_u32 s100, 1
	s_cbranch_scc0 .Lrb_skip_300
	s_barrier
.Lrb_skip_300:
.LBB0_300:
	s_add_u32 s100, s0, 0xfff80000
	s_addc_u32 s101, s1, -1
	s_add_u32 s28, s0, 0xfff80080
	s_addc_u32 s29, s1, -1
	s_add_i32 s42, 0, 0x10000
	s_cmp_eq_u32 s41, 28
	s_cselect_b32 s31, s18, s29
	s_cselect_b32 s30, s19, s28
	v_add_u32_e32 v0, s42, v199
	s_cselect_b32 s29, s27, s40
	s_cselect_b32 s28, s34, s35
	s_add_i32 s49, 0, 0x14000
	ds_read_b128 v[2:5], v0
	ds_read_b128 v[6:9], v0 offset:1024
	ds_read_b128 v[10:13], v0 offset:2048
	ds_read_b128 v[14:17], v0 offset:3072
	v_add_u32_e32 v0, s49, v199
	ds_read_b128 v[146:149], v0
	ds_read_b128 v[150:153], v0 offset:1024
	ds_read_b128 v[154:157], v0 offset:2048
	ds_read_b128 v[158:161], v0 offset:3072
	s_mov_b32 m0, s15
	ds_read_b128 v[174:177], v250
	ds_read_b128 v[178:181], v250 offset:1024
	ds_read_b128 v[182:185], v250 offset:2048
	ds_read_b128 v[186:189], v250 offset:3072
	ds_read_b128 v[190:193], v250 offset:4096
	ds_read_b128 v[200:203], v250 offset:5120
	ds_read_b128 v[204:207], v250 offset:6144
	ds_read_b128 v[208:211], v250 offset:7168
	global_load_lds_dwordx4 v162, s[100:101]
	s_mov_b32 m0, s88
	s_nop 0
	global_load_lds_dwordx4 v166, s[100:101]
	s_add_i32 m0, s21, 0xc000
	s_nop 0
	global_load_lds_dwordx4 v170, s[0:1]
	s_add_i32 m0, s21, 0xe000
	s_nop 0
	global_load_lds_dwordx4 v172, s[0:1]
	s_cmp_eq_u32 s41, 28
	s_cbranch_scc1 .Lspf_w0
	s_waitcnt vmcnt(8)
	s_branch .Lspf_j0

.LBB0_383:
	s_mov_b32 s100, 0
	s_andn2_b64 vcc, exec, s[46:47]
	s_cbranch_vccnz .LBB0_295
	s_mov_b32 s100, 1
	s_branch .LBB0_295
